# baseline (speedup 1.0000x reference)
; __device__ __forceinline__ void norm_phase(ArgP a, LAS unsigned char* lds, int l, bool final_, const int tid, const int bid) {
;     ...
;     for (int row = bid * NWAVES + wave; row < SEQ; row += gridDim.x * NWAVES) {
;         const f32x4* xr = (const f32x4*)(xsrc + (size_t)row * DM);
;         f32x4 v[8]; float ss = 0.f;
; #pragma unroll
;         for (int j = 0; j < 8; ++j) { v[j] = xr[64 * j + lane]; ss += (v[j][0] * v[j][0] + v[j][1] * v[j][1]) + (v[j][2] * v[j][2] + v[j][3] * v[j][3]); }
.LBB0_525:
	s_lshl_b32 s2, s54, 3
	s_ashr_i32 s3, s12, 6
	s_add_i32 s2, s3, s2
	s_cmpk_gt_i32 s2, 0x3fff
	s_cbranch_scc1 .LBB0_530
	v_and_b32_e32 v0, 63, v184
	v_readlane_b32 s4, v255, 25
	v_readlane_b32 s5, v255, 26
	v_lshlrev_b32_e32 v180, 16, v0
	v_lshl_add_u32 v28, s4, 3, v0
	v_lshl_add_u64 v[2:3], s[72:73], 0, v[180:181]
	s_mov_b64 s[4:5], 0x8700000
	v_lshlrev_b32_e32 v180, 3, v0
	v_lshl_add_u32 v37, v0, 4, 0
	v_lshl_add_u64 v[30:31], v[2:3], 0, s[4:5]
	v_or_b32_e32 v2, 0x100, v0
	v_or_b32_e32 v4, 0x140, v0
	v_or_b32_e32 v6, 0x180, v0
	v_or_b32_e32 v8, 0x1c0, v0
	v_lshl_add_u64 v[10:11], s[72:73], 0, v[180:181]
	s_mov_b64 s[4:5], 0x8a00000
	v_add_u32_e32 v38, 0x4000, v37
	v_cmp_gt_u32_e64 s[6:7], 8, v0
	v_ashrrev_i32_e32 v29, 31, v28
	v_cmp_eq_u32_e64 s[8:9], 7, v0
	v_cmp_eq_u32_e64 s[10:11], 6, v0
	v_cmp_eq_u32_e64 s[12:13], 5, v0
	v_cmp_eq_u32_e64 s[14:15], 4, v0
	v_cmp_eq_u32_e64 s[16:17], 3, v0
	v_cmp_eq_u32_e64 s[18:19], 2, v0
	v_cmp_eq_u32_e64 s[20:21], 1, v0
	v_lshl_add_u64 v[32:33], v[10:11], 0, s[4:5]
	v_lshlrev_b32_e32 v39, 4, v0
	v_lshlrev_b32_e32 v40, 4, v2
	v_lshlrev_b32_e32 v41, 4, v4
	v_lshlrev_b32_e32 v42, 4, v6
	v_lshlrev_b32_e32 v43, 4, v8
	s_ashr_i32 s3, s2, 31
	s_lshl_b64 s[4:5], s[2:3], 13
	s_waitcnt lgkmcnt(0)
	s_add_u32 s4, s0, s4
	s_addc_u32 s5, s1, s5
	global_load_dwordx4 v[82:85], v39, s[4:5]
	global_load_dwordx4 v[86:89], v39, s[4:5] offset:1024
	global_load_dwordx4 v[90:93], v39, s[4:5] offset:2048
	global_load_dwordx4 v[94:97], v39, s[4:5] offset:3072
	global_load_dwordx4 v[98:101], v40, s[4:5]
	global_load_dwordx4 v[102:105], v41, s[4:5]
	global_load_dwordx4 v[106:109], v42, s[4:5]
	global_load_dwordx4 v[110:113], v43, s[4:5]
	s_branch .LBB0_528

; #define LAS __attribute__((address_space(3)))
; __device__ __forceinline__ unsigned cvt_pk_bf16(float lo, float hi) { unsigned r; asm volatile("v_cvt_pk_bf16_f32 %0, %1, %2" : "=v"(r) : "v"(lo), "v"(hi)); return r; }
; __device__ __forceinline__ void norm_phase(ArgP a, LAS unsigned char* lds, int l, bool final_, const int tid, const int bid) {
;     ...
;     for (int row = bid * NWAVES + wave; row < SEQ; row += gridDim.x * NWAVES) {
;         const f32x4* xr = (const f32x4*)(xsrc + (size_t)row * DM);
;         f32x4 v[8]; float ss = 0.f;
; #pragma unroll
;         for (int j = 0; j < 8; ++j) { v[j] = xr[64 * j + lane]; ss += (v[j][0] * v[j][0] + v[j][1] * v[j][1]) + (v[j][2] * v[j][2] + v[j][3] * v[j][3]); }
;         ss = wave_sum(ss);
;         const float rstd = 1.f / sqrtf(ss * (1.f / DM) + 1e-6f);
;         if (final_) {
;             f32x4* orow = (f32x4*)(a->out + (size_t)row * DM);
; #pragma unroll
;             for (int j = 0; j < 8; ++j) { const f32x4 a1 = ((const LAS f32x4*)A1)[64 * j + lane]; orow[64 * j + lane] = v[j] * rstd * a1; }
;         } else {
;             float fd[8];
; #pragma unroll
;             for (int q = 0; q < 8; ++q) fd[q] = 0.f;
;             u32x2* hrow = (u32x2*)(H + (size_t)row * DM);
; #pragma unroll
;             for (int j = 0; j < 8; ++j) {
;                 const f32x4 a1 = ((const LAS f32x4*)A1)[64 * j + lane], a2 = ((const LAS f32x4*)A2)[64 * j + lane];
;                 const f32x4 h = v[j] * rstd * a1 + a2;
;                 u32x2 w; w.x = cvt_pk_bf16(h[0], h[1]); w.y = cvt_pk_bf16(h[2], h[3]); hrow[64 * j + lane] = w;
; #pragma unroll
;                 for (int q = 0; q < 8; ++q) { const f32x4 wf = ((const LAS f32x4*)WFt)[q * 512 + 64 * j + lane]; fd[q] += (h[0] * wf[0] + h[1] * wf[1]) + (h[2] * wf[2] + h[3] * wf[3]); }
;             }
.LBB0_528:
	s_waitcnt vmcnt(0) lgkmcnt(0)
	v_mov_b64_e32 v[44:45], v[82:83]
	v_mov_b64_e32 v[46:47], v[84:85]
	v_mov_b64_e32 v[24:25], v[86:87]
	v_mov_b64_e32 v[26:27], v[88:89]
	v_mov_b64_e32 v[20:21], v[90:91]
	v_mov_b64_e32 v[22:23], v[92:93]
	v_mov_b64_e32 v[16:17], v[94:95]
	v_mov_b64_e32 v[18:19], v[96:97]
	v_mov_b64_e32 v[12:13], v[98:99]
	v_mov_b64_e32 v[14:15], v[100:101]
	v_mov_b64_e32 v[8:9], v[102:103]
	v_mov_b64_e32 v[10:11], v[104:105]
	v_mov_b64_e32 v[4:5], v[106:107]
	v_mov_b64_e32 v[6:7], v[108:109]
	v_mov_b64_e32 v[0:1], v[110:111]
	v_mov_b64_e32 v[2:3], v[112:113]
	s_add_i32 s3, s2, s88
	s_cmpk_lt_i32 s3, 0x4000
	s_cbranch_scc0 .Lrow_nopf
	s_mov_b32 s4, s3
	s_ashr_i32 s5, s4, 31
	s_lshl_b64 s[4:5], s[4:5], 13
	s_add_u32 s4, s0, s4
	s_addc_u32 s5, s1, s5
	global_load_dwordx4 v[82:85], v39, s[4:5]
	global_load_dwordx4 v[86:89], v39, s[4:5] offset:1024
	global_load_dwordx4 v[90:93], v39, s[4:5] offset:2048
	global_load_dwordx4 v[94:97], v39, s[4:5] offset:3072
	global_load_dwordx4 v[98:101], v40, s[4:5]
	global_load_dwordx4 v[102:105], v41, s[4:5]
	global_load_dwordx4 v[106:109], v42, s[4:5]
	global_load_dwordx4 v[110:113], v43, s[4:5]
.Lrow_nopf:
	s_ashr_i32 s3, s2, 31
	s_lshl_b64 s[4:5], s[2:3], 12
	v_mul_f32_e32 v34, v45, v45
	v_mul_f32_e32 v35, v47, v47
	v_mul_f32_e32 v36, v25, v25
	v_mul_f32_e32 v48, v27, v27
	v_mul_f32_e32 v49, v21, v21
	v_mul_f32_e32 v50, v23, v23
	v_fmac_f32_e32 v34, v44, v44
	v_fmac_f32_e32 v35, v46, v46
	v_fmac_f32_e32 v36, v24, v24
	v_fmac_f32_e32 v48, v26, v26
	v_mul_f32_e32 v51, v17, v17
	v_mul_f32_e32 v52, v19, v19
	v_fmac_f32_e32 v49, v20, v20
	v_fmac_f32_e32 v50, v22, v22
	v_add_f32_e32 v34, v34, v35
	v_add_f32_e32 v35, v36, v48
	v_mul_f32_e32 v53, v13, v13
	v_mul_f32_e32 v54, v15, v15
	v_fmac_f32_e32 v51, v16, v16
	v_fmac_f32_e32 v52, v18, v18
	v_add_f32_e32 v36, v49, v50
	v_add_f32_e32 v34, v34, v35
	v_mul_f32_e32 v55, v9, v9
	v_mul_f32_e32 v56, v11, v11
	v_fmac_f32_e32 v53, v12, v12
	v_fmac_f32_e32 v54, v14, v14
	v_add_f32_e32 v48, v51, v52
	v_add_f32_e32 v34, v34, v36
	v_mul_f32_e32 v57, v5, v5
	v_mul_f32_e32 v58, v7, v7
	v_fmac_f32_e32 v55, v8, v8
	v_fmac_f32_e32 v56, v10, v10
	v_add_f32_e32 v49, v53, v54
	v_add_f32_e32 v34, v34, v48
	v_mul_f32_e32 v59, v1, v1
	v_mul_f32_e32 v60, v3, v3
	v_fmac_f32_e32 v57, v4, v4
	v_fmac_f32_e32 v58, v6, v6
	v_add_f32_e32 v50, v55, v56
	v_add_f32_e32 v34, v34, v49
	v_fmac_f32_e32 v59, v0, v0
	v_fmac_f32_e32 v60, v2, v2
	v_add_f32_e32 v51, v57, v58
	v_add_f32_e32 v34, v34, v50
	v_add_f32_e32 v52, v59, v60
	v_add_f32_e32 v34, v34, v51
	v_add_f32_e32 v34, v34, v52
	ds_swizzle_b32 v35, v34 offset:swizzle(SWAP,1)
	ds_read_b128 v[48:51], v37
	ds_read_b128 v[52:55], v37 offset:8192
	s_waitcnt lgkmcnt(2)
	v_add_f32_e32 v34, v34, v35
	ds_swizzle_b32 v35, v34 offset:swizzle(SWAP,2)
	s_waitcnt lgkmcnt(0)
	v_add_f32_e32 v34, v34, v35
	ds_swizzle_b32 v35, v34 offset:swizzle(SWAP,4)
	s_waitcnt lgkmcnt(0)
	v_add_f32_e32 v34, v34, v35
	ds_swizzle_b32 v35, v34 offset:swizzle(SWAP,8)
	s_waitcnt lgkmcnt(0)
	v_add_f32_e32 v34, v34, v35
	ds_swizzle_b32 v35, v34 offset:swizzle(SWAP,16)
	s_waitcnt lgkmcnt(0)
	v_add_f32_e32 v34, v34, v35
	v_mov_b32_e32 v35, v34
	s_nop 1
	v_permlane32_swap_b32_e32 v34, v35
	v_add_f32_e32 v34, v34, v35
	v_fmamk_f32 v34, v34, 0x3a000000, v187
	v_mul_f32_e32 v35, 0x4f800000, v34
	v_cmp_gt_f32_e32 vcc, s94, v34
	s_nop 1
	v_cndmask_b32_e32 v34, v34, v35, vcc
	v_sqrt_f32_e32 v35, v34
	s_nop 0
	v_add_u32_e32 v36, -1, v35
	v_add_u32_e32 v56, 1, v35
	v_fma_f32 v57, -v36, v35, v34
	v_fma_f32 v58, -v56, v35, v34
	v_cmp_ge_f32_e64 s[22:23], 0, v57
	s_nop 1
	v_cndmask_b32_e64 v35, v35, v36, s[22:23]
	v_cmp_lt_f32_e64 s[22:23], 0, v58
	s_nop 1
	v_cndmask_b32_e64 v35, v35, v56, s[22:23]
	v_mul_f32_e32 v36, 0x37800000, v35
	v_cndmask_b32_e32 v35, v35, v36, vcc
	v_cmp_class_f32_e32 vcc, v34, v194
	s_nop 1
	v_cndmask_b32_e32 v36, v35, v34, vcc
	v_div_scale_f32 v56, s[22:23], v36, v36, 1.0
	v_rcp_f32_e32 v57, v56
	v_div_scale_f32 v58, vcc, 1.0, v36, 1.0
	v_lshl_add_u64 v[34:35], v[32:33], 0, s[4:5]
	v_fma_f32 v59, -v56, v57, 1.0
	v_fmac_f32_e32 v57, v59, v57
	v_mul_f32_e32 v59, v58, v57
	v_fma_f32 v60, -v56, v59, v58
	v_fmac_f32_e32 v59, v60, v57
	v_fma_f32 v56, -v56, v59, v58
	v_div_fmas_f32 v56, v56, v57, v59
	v_div_fixup_f32 v36, v56, v36, 1.0
	v_pk_mul_f32 v[44:45], v[44:45], v[36:37] op_sel_hi:[1,0]
	v_pk_mul_f32 v[46:47], v[46:47], v[36:37] op_sel_hi:[1,0]
	v_pk_fma_f32 v[78:79], v[48:49], v[44:45], v[52:53]
	v_pk_fma_f32 v[76:77], v[50:51], v[46:47], v[54:55]
	v_cvt_pk_bf16_f32 v80, v78, v79
	v_pk_mul_f32 v[24:25], v[24:25], v[36:37] op_sel_hi:[1,0]
	v_cvt_pk_bf16_f32 v81, v76, v77
	ds_read_b128 v[44:47], v37 offset:16384
	ds_read_b128 v[48:51], v37 offset:24576
	ds_read_b128 v[52:55], v37 offset:32768
	ds_read_b128 v[56:59], v37 offset:40960
	ds_read_b128 v[60:63], v37 offset:49152
	ds_read_b128 v[64:67], v37 offset:57344
	ds_read_b128 v[68:71], v38 offset:49152
	ds_read_b128 v[72:75], v38 offset:57344
	s_waitcnt lgkmcnt(7)
	v_mul_f32_e32 v45, v45, v79
	v_mul_f32_e32 v47, v47, v77
	s_waitcnt lgkmcnt(6)
	v_mul_f32_e32 v49, v49, v79
	v_mul_f32_e32 v51, v51, v77
	s_waitcnt lgkmcnt(5)
	v_mul_f32_e32 v53, v53, v79
	v_mul_f32_e32 v55, v55, v77
	s_waitcnt lgkmcnt(4)
	v_mul_f32_e32 v57, v57, v79
	v_mul_f32_e32 v59, v59, v77
	s_waitcnt lgkmcnt(3)
	v_mul_f32_e32 v61, v61, v79
	v_mul_f32_e32 v63, v63, v77
	s_waitcnt lgkmcnt(2)
	v_mul_f32_e32 v65, v65, v79
	v_mul_f32_e32 v67, v67, v77
	s_waitcnt lgkmcnt(1)
; #define LAS __attribute__((address_space(3)))
; __device__ __forceinline__ unsigned cvt_pk_bf16(float lo, float hi) { unsigned r; asm volatile("v_cvt_pk_bf16_f32 %0, %1, %2" : "=v"(r) : "v"(lo), "v"(hi)); return r; }
; __device__ __forceinline__ void norm_phase(ArgP a, LAS unsigned char* lds, int l, bool final_, const int tid, const int bid) {
;     ...
;             for (int j = 0; j < 8; ++j) {
;                 const f32x4 a1 = ((const LAS f32x4*)A1)[64 * j + lane], a2 = ((const LAS f32x4*)A2)[64 * j + lane];
;                 const f32x4 h = v[j] * rstd * a1 + a2;
;                 u32x2 w; w.x = cvt_pk_bf16(h[0], h[1]); w.y = cvt_pk_bf16(h[2], h[3]); hrow[64 * j + lane] = w;
; #pragma unroll
;                 for (int q = 0; q < 8; ++q) { const f32x4 wf = ((const LAS f32x4*)WFt)[q * 512 + 64 * j + lane]; fd[q] += (h[0] * wf[0] + h[1] * wf[1]) + (h[2] * wf[2] + h[3] * wf[3]); }
;             }
	v_mul_f32_e32 v69, v79, v69
	v_mul_f32_e32 v71, v77, v71
	v_fmac_f32_e32 v45, v44, v78
	v_fmac_f32_e32 v47, v46, v76
	v_fmac_f32_e32 v49, v48, v78
	v_fmac_f32_e32 v51, v50, v76
	v_fmac_f32_e32 v53, v52, v78
	v_fmac_f32_e32 v55, v54, v76
	v_fmac_f32_e32 v57, v56, v78
	v_fmac_f32_e32 v59, v58, v76
	v_fmac_f32_e32 v61, v60, v78
	v_fmac_f32_e32 v63, v62, v76
	v_fmac_f32_e32 v65, v64, v78
	v_fmac_f32_e32 v67, v66, v76
	v_fmac_f32_e32 v69, v78, v68
	v_fmac_f32_e32 v71, v76, v70
	global_store_dwordx2 v[34:35], v[80:81], off
	v_add_f32_e32 v44, v45, v47
	v_add_f32_e32 v45, v49, v51
	v_add_f32_e32 v46, v53, v55
	v_add_f32_e32 v47, v57, v59
	v_add_f32_e32 v48, v61, v63
	v_add_f32_e32 v49, v65, v67
	v_add_f32_e32 v50, v69, v71
	v_add_f32_e32 v54, 0, v44
	v_add_f32_e32 v55, 0, v45
	v_add_f32_e32 v56, 0, v46
	v_add_f32_e32 v57, 0, v47
	v_add_f32_e32 v58, 0, v48
	v_add_f32_e32 v59, 0, v49
	v_add_f32_e32 v60, 0, v50
	ds_read_b128 v[44:47], v37 offset:1024
	ds_read_b128 v[48:51], v37 offset:9216
	v_pk_mul_f32 v[26:27], v[26:27], v[36:37] op_sel_hi:[1,0]
	s_waitcnt lgkmcnt(2)
	v_mul_f32_e32 v61, v79, v73
	v_mul_f32_e32 v62, v77, v75
	v_fmac_f32_e32 v61, v78, v72
	s_waitcnt lgkmcnt(0)
	v_pk_fma_f32 v[52:53], v[26:27], v[46:47], v[50:51]
	v_pk_fma_f32 v[48:49], v[24:25], v[44:45], v[48:49]
	v_fmac_f32_e32 v62, v76, v74
	v_cvt_pk_bf16_f32 v44, v48, v49
	v_cvt_pk_bf16_f32 v45, v52, v53
	ds_read_b128 v[24:27], v37 offset:17408
	v_add_f32_e32 v46, v61, v62
	v_add_f32_e32 v61, 0, v46
	global_store_dwordx2 v[34:35], v[44:45], off offset:512
	ds_read_b128 v[44:47], v37 offset:25600
	s_waitcnt lgkmcnt(1)
	v_mul_f32_e32 v25, v49, v25
	v_fmac_f32_e32 v25, v48, v24
	v_mul_f32_e32 v24, v53, v27
	v_fmac_f32_e32 v24, v52, v26
	v_add_f32_e32 v24, v25, v24
	s_waitcnt lgkmcnt(0)
	v_mul_f32_e32 v45, v49, v45
	v_add_f32_e32 v54, v54, v24
	v_fmac_f32_e32 v45, v48, v44
	v_mul_f32_e32 v44, v53, v47
	ds_read_b128 v[24:27], v37 offset:33792
	v_fmac_f32_e32 v44, v52, v46
	v_add_f32_e32 v44, v45, v44
	v_add_f32_e32 v55, v55, v44
	ds_read_b128 v[44:47], v37 offset:41984
	s_waitcnt lgkmcnt(1)
	v_mul_f32_e32 v25, v49, v25
	v_fmac_f32_e32 v25, v48, v24
	v_mul_f32_e32 v24, v53, v27
	v_fmac_f32_e32 v24, v52, v26
	v_add_f32_e32 v24, v25, v24
	s_waitcnt lgkmcnt(0)
	v_mul_f32_e32 v45, v49, v45
	v_add_f32_e32 v56, v56, v24
	v_fmac_f32_e32 v45, v48, v44
	v_mul_f32_e32 v44, v53, v47
	ds_read_b128 v[24:27], v37 offset:50176
	v_fmac_f32_e32 v44, v52, v46
	v_add_f32_e32 v44, v45, v44
	v_add_f32_e32 v57, v57, v44
	ds_read_b128 v[44:47], v37 offset:58368
	s_waitcnt lgkmcnt(1)
	v_mul_f32_e32 v25, v49, v25
	v_fmac_f32_e32 v25, v48, v24
	v_mul_f32_e32 v24, v53, v27
	v_fmac_f32_e32 v24, v52, v26
	v_add_f32_e32 v24, v25, v24
	s_waitcnt lgkmcnt(0)
	v_mul_f32_e32 v45, v49, v45
	v_add_f32_e32 v58, v58, v24
	v_fmac_f32_e32 v45, v48, v44
	v_mul_f32_e32 v44, v53, v47
	ds_read_b128 v[24:27], v38 offset:50176
	v_fmac_f32_e32 v44, v52, v46
	v_add_f32_e32 v44, v45, v44
	v_add_f32_e32 v59, v59, v44
	ds_read_b128 v[44:47], v38 offset:58368
	s_waitcnt lgkmcnt(1)
	v_mul_f32_e32 v25, v49, v25
	v_fmac_f32_e32 v25, v48, v24
	v_mul_f32_e32 v24, v53, v27
	v_fmac_f32_e32 v24, v52, v26
	v_add_f32_e32 v24, v25, v24
	s_waitcnt lgkmcnt(0)
	v_mul_f32_e32 v62, v49, v45
	v_add_f32_e32 v60, v60, v24
	v_fmac_f32_e32 v62, v48, v44
	ds_read_b128 v[24:27], v37 offset:2048
	ds_read_b128 v[48:51], v37 offset:10240
	v_pk_mul_f32 v[20:21], v[20:21], v[36:37] op_sel_hi:[1,0]
	v_pk_mul_f32 v[22:23], v[22:23], v[36:37] op_sel_hi:[1,0]
	v_mul_f32_e32 v47, v53, v47
	v_fmac_f32_e32 v47, v52, v46
	s_waitcnt lgkmcnt(0)
	v_pk_fma_f32 v[50:51], v[22:23], v[26:27], v[50:51]
	v_pk_fma_f32 v[44:45], v[20:21], v[24:25], v[48:49]
	v_add_f32_e32 v26, v62, v47
	v_cvt_pk_bf16_f32 v24, v44, v45
	v_cvt_pk_bf16_f32 v25, v50, v51
	ds_read_b128 v[20:23], v37 offset:18432
	v_add_f32_e32 v48, v61, v26
	global_store_dwordx2 v[34:35], v[24:25], off offset:1024
	ds_read_b128 v[24:27], v37 offset:26624
	v_pk_mul_f32 v[16:17], v[16:17], v[36:37] op_sel_hi:[1,0]
	s_waitcnt lgkmcnt(1)
	v_mul_f32_e32 v21, v45, v21
	v_fmac_f32_e32 v21, v44, v20
	v_mul_f32_e32 v20, v51, v23
	v_fmac_f32_e32 v20, v50, v22
	v_add_f32_e32 v20, v21, v20
	s_waitcnt lgkmcnt(0)
	v_mul_f32_e32 v25, v45, v25
	v_add_f32_e32 v49, v54, v20
	v_fmac_f32_e32 v25, v44, v24
	v_mul_f32_e32 v24, v51, v27
	ds_read_b128 v[20:23], v37 offset:34816
	v_fmac_f32_e32 v24, v50, v26
	v_add_f32_e32 v24, v25, v24
	v_add_f32_e32 v52, v55, v24
	ds_read_b128 v[24:27], v37 offset:43008
	s_waitcnt lgkmcnt(1)
	v_mul_f32_e32 v21, v45, v21
	v_fmac_f32_e32 v21, v44, v20
	v_mul_f32_e32 v20, v51, v23
	v_fmac_f32_e32 v20, v50, v22
	v_add_f32_e32 v20, v21, v20
	s_waitcnt lgkmcnt(0)
	v_mul_f32_e32 v25, v45, v25
	v_add_f32_e32 v53, v56, v20
	v_fmac_f32_e32 v25, v44, v24
	v_mul_f32_e32 v24, v51, v27
	ds_read_b128 v[20:23], v37 offset:51200
	v_fmac_f32_e32 v24, v50, v26
	v_add_f32_e32 v24, v25, v24
	v_add_f32_e32 v54, v57, v24
	ds_read_b128 v[24:27], v37 offset:59392
	s_waitcnt lgkmcnt(1)
	v_mul_f32_e32 v21, v45, v21
	v_fmac_f32_e32 v21, v44, v20
	v_mul_f32_e32 v20, v51, v23
	v_fmac_f32_e32 v20, v50, v22
	v_add_f32_e32 v20, v21, v20
	s_waitcnt lgkmcnt(0)
	v_mul_f32_e32 v25, v45, v25
	v_add_f32_e32 v55, v58, v20
	v_fmac_f32_e32 v25, v44, v24
	v_mul_f32_e32 v24, v51, v27
	ds_read_b128 v[20:23], v38 offset:51200
	v_fmac_f32_e32 v24, v50, v26
	v_add_f32_e32 v24, v25, v24
	v_add_f32_e32 v56, v59, v24
	ds_read_b128 v[24:27], v38 offset:59392
	s_waitcnt lgkmcnt(1)
	v_mul_f32_e32 v21, v45, v21
	v_fmac_f32_e32 v21, v44, v20
	v_mul_f32_e32 v20, v51, v23
	v_fmac_f32_e32 v20, v50, v22
	v_add_f32_e32 v20, v21, v20
	s_waitcnt lgkmcnt(0)
; #define LAS __attribute__((address_space(3)))
; __device__ __forceinline__ unsigned cvt_pk_bf16(float lo, float hi) { unsigned r; asm volatile("v_cvt_pk_bf16_f32 %0, %1, %2" : "=v"(r) : "v"(lo), "v"(hi)); return r; }
; __device__ __forceinline__ void norm_phase(ArgP a, LAS unsigned char* lds, int l, bool final_, const int tid, const int bid) {
;     ...
;             for (int j = 0; j < 8; ++j) {
;                 const f32x4 a1 = ((const LAS f32x4*)A1)[64 * j + lane], a2 = ((const LAS f32x4*)A2)[64 * j + lane];
;                 const f32x4 h = v[j] * rstd * a1 + a2;
;                 u32x2 w; w.x = cvt_pk_bf16(h[0], h[1]); w.y = cvt_pk_bf16(h[2], h[3]); hrow[64 * j + lane] = w;
; #pragma unroll
;                 for (int q = 0; q < 8; ++q) { const f32x4 wf = ((const LAS f32x4*)WFt)[q * 512 + 64 * j + lane]; fd[q] += (h[0] * wf[0] + h[1] * wf[1]) + (h[2] * wf[2] + h[3] * wf[3]); }
;             }
	v_mul_f32_e32 v58, v45, v25
	v_add_f32_e32 v57, v60, v20
	v_fmac_f32_e32 v58, v44, v24
	ds_read_b128 v[20:23], v37 offset:3072
	ds_read_b128 v[44:47], v37 offset:11264
	v_pk_mul_f32 v[18:19], v[18:19], v[36:37] op_sel_hi:[1,0]
	v_mul_f32_e32 v27, v51, v27
	v_fmac_f32_e32 v27, v50, v26
	v_pk_mul_f32 v[12:13], v[12:13], v[36:37] op_sel_hi:[1,0]
	s_waitcnt lgkmcnt(0)
	v_pk_fma_f32 v[46:47], v[18:19], v[22:23], v[46:47]
	v_pk_fma_f32 v[24:25], v[16:17], v[20:21], v[44:45]
	v_add_f32_e32 v22, v58, v27
	v_cvt_pk_bf16_f32 v20, v24, v25
	v_cvt_pk_bf16_f32 v21, v46, v47
	ds_read_b128 v[16:19], v37 offset:19456
	v_add_f32_e32 v44, v48, v22
	global_store_dwordx2 v[34:35], v[20:21], off offset:1536
	ds_read_b128 v[20:23], v37 offset:27648
	v_pk_mul_f32 v[14:15], v[14:15], v[36:37] op_sel_hi:[1,0]
	s_waitcnt lgkmcnt(1)
	v_mul_f32_e32 v17, v25, v17
	v_fmac_f32_e32 v17, v24, v16
	v_mul_f32_e32 v16, v47, v19
	v_fmac_f32_e32 v16, v46, v18
	v_add_f32_e32 v16, v17, v16
	s_waitcnt lgkmcnt(0)
	v_mul_f32_e32 v21, v25, v21
	v_add_f32_e32 v45, v49, v16
	v_fmac_f32_e32 v21, v24, v20
	v_mul_f32_e32 v20, v47, v23
	ds_read_b128 v[16:19], v37 offset:35840
	v_fmac_f32_e32 v20, v46, v22
	v_add_f32_e32 v20, v21, v20
	v_add_f32_e32 v48, v52, v20
	ds_read_b128 v[20:23], v37 offset:44032
	s_waitcnt lgkmcnt(1)
	v_mul_f32_e32 v17, v25, v17
	v_fmac_f32_e32 v17, v24, v16
	v_mul_f32_e32 v16, v47, v19
	v_fmac_f32_e32 v16, v46, v18
	v_add_f32_e32 v16, v17, v16
	s_waitcnt lgkmcnt(0)
	v_mul_f32_e32 v21, v25, v21
	v_add_f32_e32 v49, v53, v16
	v_fmac_f32_e32 v21, v24, v20
	v_mul_f32_e32 v20, v47, v23
	ds_read_b128 v[16:19], v37 offset:52224
	v_fmac_f32_e32 v20, v46, v22
	v_add_f32_e32 v20, v21, v20
	v_add_f32_e32 v50, v54, v20
	ds_read_b128 v[20:23], v37 offset:60416
	s_waitcnt lgkmcnt(1)
	v_mul_f32_e32 v17, v25, v17
	v_fmac_f32_e32 v17, v24, v16
	v_mul_f32_e32 v16, v47, v19
	v_fmac_f32_e32 v16, v46, v18
	v_add_f32_e32 v16, v17, v16
	s_waitcnt lgkmcnt(0)
	v_mul_f32_e32 v21, v25, v21
	v_add_f32_e32 v51, v55, v16
	v_fmac_f32_e32 v21, v24, v20
	v_mul_f32_e32 v20, v47, v23
	ds_read_b128 v[16:19], v38 offset:52224
	v_fmac_f32_e32 v20, v46, v22
	v_add_f32_e32 v20, v21, v20
	v_add_f32_e32 v52, v56, v20
	ds_read_b128 v[20:23], v38 offset:60416
	s_waitcnt lgkmcnt(1)
	v_mul_f32_e32 v17, v25, v17
	v_fmac_f32_e32 v17, v24, v16
	v_mul_f32_e32 v16, v47, v19
	v_fmac_f32_e32 v16, v46, v18
	v_add_f32_e32 v16, v17, v16
	s_waitcnt lgkmcnt(0)
	v_mul_f32_e32 v54, v25, v21
	v_add_f32_e32 v53, v57, v16
	v_fmac_f32_e32 v54, v24, v20
	ds_read_b128 v[16:19], v37 offset:4096
	ds_read_b128 v[24:27], v37 offset:12288
	v_mul_f32_e32 v23, v47, v23
	v_fmac_f32_e32 v23, v46, v22
	v_pk_mul_f32 v[8:9], v[8:9], v[36:37] op_sel_hi:[1,0]
	v_pk_mul_f32 v[10:11], v[10:11], v[36:37] op_sel_hi:[1,0]
	s_waitcnt lgkmcnt(0)
	v_pk_fma_f32 v[26:27], v[14:15], v[18:19], v[26:27]
	v_pk_fma_f32 v[20:21], v[12:13], v[16:17], v[24:25]
	v_add_f32_e32 v18, v54, v23
	v_cvt_pk_bf16_f32 v16, v20, v21
	v_cvt_pk_bf16_f32 v17, v26, v27
	ds_read_b128 v[12:15], v37 offset:20480
	v_add_f32_e32 v24, v44, v18
	global_store_dwordx2 v[34:35], v[16:17], off offset:2048
	ds_read_b128 v[16:19], v37 offset:28672
	v_pk_mul_f32 v[4:5], v[4:5], v[36:37] op_sel_hi:[1,0]
	s_waitcnt lgkmcnt(1)
	v_mul_f32_e32 v13, v21, v13
	v_fmac_f32_e32 v13, v20, v12
	v_mul_f32_e32 v12, v27, v15
	v_fmac_f32_e32 v12, v26, v14
	v_add_f32_e32 v12, v13, v12
	s_waitcnt lgkmcnt(0)
	v_mul_f32_e32 v17, v21, v17
	v_add_f32_e32 v25, v45, v12
	v_fmac_f32_e32 v17, v20, v16
	v_mul_f32_e32 v16, v27, v19
	ds_read_b128 v[12:15], v37 offset:36864
	v_fmac_f32_e32 v16, v26, v18
	v_add_f32_e32 v16, v17, v16
	v_add_f32_e32 v44, v48, v16
	ds_read_b128 v[16:19], v37 offset:45056
	s_waitcnt lgkmcnt(1)
	v_mul_f32_e32 v13, v21, v13
	v_fmac_f32_e32 v13, v20, v12
	v_mul_f32_e32 v12, v27, v15
	v_fmac_f32_e32 v12, v26, v14
	v_add_f32_e32 v12, v13, v12
	s_waitcnt lgkmcnt(0)
	v_mul_f32_e32 v17, v21, v17
	v_add_f32_e32 v45, v49, v12
	v_fmac_f32_e32 v17, v20, v16
	v_mul_f32_e32 v16, v27, v19
	ds_read_b128 v[12:15], v37 offset:53248
	v_fmac_f32_e32 v16, v26, v18
	v_add_f32_e32 v16, v17, v16
	v_add_f32_e32 v46, v50, v16
	ds_read_b128 v[16:19], v37 offset:61440
	s_waitcnt lgkmcnt(1)
	v_mul_f32_e32 v13, v21, v13
	v_fmac_f32_e32 v13, v20, v12
	v_mul_f32_e32 v12, v27, v15
	v_fmac_f32_e32 v12, v26, v14
	v_add_f32_e32 v12, v13, v12
	s_waitcnt lgkmcnt(0)
	v_mul_f32_e32 v17, v21, v17
	v_add_f32_e32 v47, v51, v12
	v_fmac_f32_e32 v17, v20, v16
	v_mul_f32_e32 v16, v27, v19
	ds_read_b128 v[12:15], v38 offset:53248
	v_fmac_f32_e32 v16, v26, v18
	v_add_f32_e32 v16, v17, v16
	v_add_f32_e32 v48, v52, v16
	ds_read_b128 v[16:19], v38 offset:61440
	s_waitcnt lgkmcnt(1)
	v_mul_f32_e32 v13, v21, v13
	v_fmac_f32_e32 v13, v20, v12
	v_mul_f32_e32 v12, v27, v15
	v_fmac_f32_e32 v12, v26, v14
	v_add_f32_e32 v12, v13, v12
	s_waitcnt lgkmcnt(0)
	v_mul_f32_e32 v50, v21, v17
	v_add_f32_e32 v49, v53, v12
	v_fmac_f32_e32 v50, v20, v16
	ds_read_b128 v[12:15], v37 offset:5120
	ds_read_b128 v[20:23], v37 offset:13312
	v_mul_f32_e32 v19, v27, v19
	v_fmac_f32_e32 v19, v26, v18
	v_pk_mul_f32 v[6:7], v[6:7], v[36:37] op_sel_hi:[1,0]
	v_pk_mul_f32 v[0:1], v[0:1], v[36:37] op_sel_hi:[1,0]
	s_waitcnt lgkmcnt(0)
	v_pk_fma_f32 v[22:23], v[10:11], v[14:15], v[22:23]
	v_pk_fma_f32 v[16:17], v[8:9], v[12:13], v[20:21]
	v_add_f32_e32 v14, v50, v19
	v_cvt_pk_bf16_f32 v12, v16, v17
	v_cvt_pk_bf16_f32 v13, v22, v23
	ds_read_b128 v[8:11], v37 offset:21504
	v_add_f32_e32 v20, v24, v14
	global_store_dwordx2 v[34:35], v[12:13], off offset:2560
	ds_read_b128 v[12:15], v37 offset:29696
	v_pk_mul_f32 v[2:3], v[2:3], v[36:37] op_sel_hi:[1,0]
	s_waitcnt lgkmcnt(1)
; #define LAS __attribute__((address_space(3)))
; __device__ __forceinline__ unsigned cvt_pk_bf16(float lo, float hi) { unsigned r; asm volatile("v_cvt_pk_bf16_f32 %0, %1, %2" : "=v"(r) : "v"(lo), "v"(hi)); return r; }
; __device__ __forceinline__ void norm_phase(ArgP a, LAS unsigned char* lds, int l, bool final_, const int tid, const int bid) {
;     ...
;             for (int j = 0; j < 8; ++j) {
;                 const f32x4 a1 = ((const LAS f32x4*)A1)[64 * j + lane], a2 = ((const LAS f32x4*)A2)[64 * j + lane];
;                 const f32x4 h = v[j] * rstd * a1 + a2;
;                 u32x2 w; w.x = cvt_pk_bf16(h[0], h[1]); w.y = cvt_pk_bf16(h[2], h[3]); hrow[64 * j + lane] = w;
; #pragma unroll
;                 for (int q = 0; q < 8; ++q) { const f32x4 wf = ((const LAS f32x4*)WFt)[q * 512 + 64 * j + lane]; fd[q] += (h[0] * wf[0] + h[1] * wf[1]) + (h[2] * wf[2] + h[3] * wf[3]); }
;             }
; #pragma unroll
;             for (int q = 0; q < 8; ++q) fd[q] = wave_sum(fd[q]);
	v_mul_f32_e32 v9, v17, v9
	v_fmac_f32_e32 v9, v16, v8
	v_mul_f32_e32 v8, v23, v11
	v_fmac_f32_e32 v8, v22, v10
	v_add_f32_e32 v8, v9, v8
	s_waitcnt lgkmcnt(0)
	v_mul_f32_e32 v13, v17, v13
	v_add_f32_e32 v21, v25, v8
	v_fmac_f32_e32 v13, v16, v12
	v_mul_f32_e32 v12, v23, v15
	ds_read_b128 v[8:11], v37 offset:37888
	v_fmac_f32_e32 v12, v22, v14
	v_add_f32_e32 v12, v13, v12
	v_add_f32_e32 v24, v44, v12
	ds_read_b128 v[12:15], v37 offset:46080
	s_waitcnt lgkmcnt(1)
	v_mul_f32_e32 v9, v17, v9
	v_fmac_f32_e32 v9, v16, v8
	v_mul_f32_e32 v8, v23, v11
	v_fmac_f32_e32 v8, v22, v10
	v_add_f32_e32 v8, v9, v8
	s_waitcnt lgkmcnt(0)
	v_mul_f32_e32 v13, v17, v13
	v_add_f32_e32 v25, v45, v8
	v_fmac_f32_e32 v13, v16, v12
	v_mul_f32_e32 v12, v23, v15
	ds_read_b128 v[8:11], v37 offset:54272
	v_fmac_f32_e32 v12, v22, v14
	v_add_f32_e32 v12, v13, v12
	v_add_f32_e32 v26, v46, v12
	ds_read_b128 v[12:15], v37 offset:62464
	s_waitcnt lgkmcnt(1)
	v_mul_f32_e32 v9, v17, v9
	v_fmac_f32_e32 v9, v16, v8
	v_mul_f32_e32 v8, v23, v11
	v_fmac_f32_e32 v8, v22, v10
	v_add_f32_e32 v8, v9, v8
	s_waitcnt lgkmcnt(0)
	v_mul_f32_e32 v13, v17, v13
	v_add_f32_e32 v27, v47, v8
	v_fmac_f32_e32 v13, v16, v12
	v_mul_f32_e32 v12, v23, v15
	ds_read_b128 v[8:11], v38 offset:54272
	v_fmac_f32_e32 v12, v22, v14
	v_add_f32_e32 v12, v13, v12
	v_add_f32_e32 v44, v48, v12
	ds_read_b128 v[12:15], v38 offset:62464
	s_waitcnt lgkmcnt(1)
	v_mul_f32_e32 v9, v17, v9
	v_fmac_f32_e32 v9, v16, v8
	v_mul_f32_e32 v8, v23, v11
	v_fmac_f32_e32 v8, v22, v10
	v_add_f32_e32 v8, v9, v8
	s_waitcnt lgkmcnt(0)
	v_mul_f32_e32 v46, v17, v13
	v_add_f32_e32 v45, v49, v8
	v_fmac_f32_e32 v46, v16, v12
	ds_read_b128 v[8:11], v37 offset:6144
	ds_read_b128 v[16:19], v37 offset:14336
	v_mul_f32_e32 v15, v23, v15
	v_fmac_f32_e32 v15, v22, v14
	s_waitcnt lgkmcnt(0)
	v_pk_fma_f32 v[18:19], v[6:7], v[10:11], v[18:19]
	v_pk_fma_f32 v[12:13], v[4:5], v[8:9], v[16:17]
	v_add_f32_e32 v10, v46, v15
	v_cvt_pk_bf16_f32 v8, v12, v13
	v_cvt_pk_bf16_f32 v9, v18, v19
	ds_read_b128 v[4:7], v37 offset:22528
	v_add_f32_e32 v16, v20, v10
	global_store_dwordx2 v[34:35], v[8:9], off offset:3072
	ds_read_b128 v[8:11], v37 offset:30720
	s_waitcnt lgkmcnt(1)
	v_mul_f32_e32 v5, v13, v5
	v_fmac_f32_e32 v5, v12, v4
	v_mul_f32_e32 v4, v19, v7
	v_fmac_f32_e32 v4, v18, v6
	v_add_f32_e32 v4, v5, v4
	s_waitcnt lgkmcnt(0)
	v_mul_f32_e32 v9, v13, v9
	v_add_f32_e32 v17, v21, v4
	v_fmac_f32_e32 v9, v12, v8
	v_mul_f32_e32 v8, v19, v11
	ds_read_b128 v[4:7], v37 offset:38912
	v_fmac_f32_e32 v8, v18, v10
	v_add_f32_e32 v8, v9, v8
	v_add_f32_e32 v20, v24, v8
	ds_read_b128 v[8:11], v37 offset:47104
	s_waitcnt lgkmcnt(1)
	v_mul_f32_e32 v5, v13, v5
	v_fmac_f32_e32 v5, v12, v4
	v_mul_f32_e32 v4, v19, v7
	v_fmac_f32_e32 v4, v18, v6
	v_add_f32_e32 v4, v5, v4
	s_waitcnt lgkmcnt(0)
	v_mul_f32_e32 v9, v13, v9
	v_add_f32_e32 v21, v25, v4
	v_fmac_f32_e32 v9, v12, v8
	v_mul_f32_e32 v8, v19, v11
	ds_read_b128 v[4:7], v37 offset:55296
	v_fmac_f32_e32 v8, v18, v10
	v_add_f32_e32 v8, v9, v8
	v_add_f32_e32 v22, v26, v8
	ds_read_b128 v[8:11], v37 offset:63488
	s_waitcnt lgkmcnt(1)
	v_mul_f32_e32 v5, v13, v5
	v_fmac_f32_e32 v5, v12, v4
	v_mul_f32_e32 v4, v19, v7
	v_fmac_f32_e32 v4, v18, v6
	v_add_f32_e32 v4, v5, v4
	s_waitcnt lgkmcnt(0)
	v_mul_f32_e32 v9, v13, v9
	v_add_f32_e32 v23, v27, v4
	v_fmac_f32_e32 v9, v12, v8
	v_mul_f32_e32 v8, v19, v11
	ds_read_b128 v[4:7], v38 offset:55296
	v_fmac_f32_e32 v8, v18, v10
	v_add_f32_e32 v8, v9, v8
	v_add_f32_e32 v24, v44, v8
	ds_read_b128 v[8:11], v38 offset:63488
	s_waitcnt lgkmcnt(1)
	v_mul_f32_e32 v5, v13, v5
	v_fmac_f32_e32 v5, v12, v4
	v_mul_f32_e32 v4, v19, v7
	v_fmac_f32_e32 v4, v18, v6
	v_add_f32_e32 v4, v5, v4
	s_waitcnt lgkmcnt(0)
	v_mul_f32_e32 v26, v13, v9
	v_add_f32_e32 v25, v45, v4
	v_fmac_f32_e32 v26, v12, v8
	ds_read_b128 v[4:7], v37 offset:7168
	ds_read_b128 v[12:15], v37 offset:15360
	v_mul_f32_e32 v19, v19, v11
	v_fmac_f32_e32 v19, v18, v10
	s_waitcnt lgkmcnt(0)
	v_pk_fma_f32 v[8:9], v[2:3], v[6:7], v[14:15]
	v_pk_fma_f32 v[10:11], v[0:1], v[4:5], v[12:13]
	v_add_f32_e32 v6, v26, v19
	v_cvt_pk_bf16_f32 v4, v10, v11
	v_cvt_pk_bf16_f32 v5, v8, v9
	ds_read_b128 v[0:3], v37 offset:23552
	v_add_f32_e32 v12, v16, v6
	global_store_dwordx2 v[34:35], v[4:5], off offset:3584
	ds_read_b128 v[4:7], v37 offset:31744
	s_waitcnt lgkmcnt(1)
	v_mul_f32_e32 v1, v11, v1
	v_fmac_f32_e32 v1, v10, v0
	v_mul_f32_e32 v0, v9, v3
	v_fmac_f32_e32 v0, v8, v2
	v_add_f32_e32 v0, v1, v0
	v_add_f32_e32 v13, v17, v0
	ds_read_b128 v[0:3], v37 offset:39936
	s_waitcnt lgkmcnt(1)
	v_mul_f32_e32 v5, v11, v5
	v_fmac_f32_e32 v5, v10, v4
	v_mul_f32_e32 v4, v9, v7
	v_fmac_f32_e32 v4, v8, v6
	v_add_f32_e32 v4, v5, v4
	v_add_f32_e32 v14, v20, v4
	ds_read_b128 v[4:7], v37 offset:48128
	s_waitcnt lgkmcnt(1)
	v_mul_f32_e32 v1, v11, v1
	v_fmac_f32_e32 v1, v10, v0
	v_mul_f32_e32 v0, v9, v3
	v_fmac_f32_e32 v0, v8, v2
	v_add_f32_e32 v0, v1, v0
	v_add_f32_e32 v15, v21, v0
	ds_read_b128 v[0:3], v37 offset:56320
	s_waitcnt lgkmcnt(1)
	v_mul_f32_e32 v5, v11, v5
	v_fmac_f32_e32 v5, v10, v4
	v_mul_f32_e32 v4, v9, v7
	v_fmac_f32_e32 v4, v8, v6
	v_add_f32_e32 v4, v5, v4
	v_add_f32_e32 v16, v22, v4
	ds_read_b128 v[4:7], v37 offset:64512
	s_waitcnt lgkmcnt(1)
	v_mul_f32_e32 v1, v11, v1
	v_fmac_f32_e32 v1, v10, v0
	v_mul_f32_e32 v0, v9, v3
	v_fmac_f32_e32 v0, v8, v2
	v_add_f32_e32 v0, v1, v0
	v_add_f32_e32 v17, v23, v0
	ds_read_b128 v[0:3], v38 offset:56320
	s_waitcnt lgkmcnt(1)
	v_mul_f32_e32 v5, v11, v5
	v_fmac_f32_e32 v5, v10, v4
	v_mul_f32_e32 v4, v9, v7
	ds_swizzle_b32 v19, v13 offset:swizzle(SWAP,1)
	v_fmac_f32_e32 v4, v8, v6
	v_add_f32_e32 v4, v5, v4
	v_add_f32_e32 v18, v24, v4
	ds_read_b128 v[4:7], v38 offset:64512
	s_waitcnt lgkmcnt(2)
; __device__ __forceinline__ void norm_phase(ArgP a, LAS unsigned char* lds, int l, bool final_, const int tid, const int bid) {
;     ...
;             for (int q = 0; q < 8; ++q) fd[q] = wave_sum(fd[q]);
;             float z = fd[0];
; #pragma unroll
;             for (int q = 1; q < 8; ++q) z = (lane == q) ? fd[q] : z;
	v_mul_f32_e32 v1, v11, v1
	v_fmac_f32_e32 v1, v10, v0
	v_mul_f32_e32 v0, v9, v3
	v_fmac_f32_e32 v0, v8, v2
	s_waitcnt lgkmcnt(1)
	v_add_f32_e32 v2, v13, v19
	ds_swizzle_b32 v3, v2 offset:swizzle(SWAP,2)
	v_add_f32_e32 v0, v1, v0
	ds_swizzle_b32 v1, v14 offset:swizzle(SWAP,1)
	v_add_f32_e32 v13, v25, v0
	s_waitcnt lgkmcnt(2)
	v_mul_f32_e32 v0, v11, v5
	s_waitcnt lgkmcnt(1)
	v_add_f32_e32 v2, v2, v3
	ds_swizzle_b32 v3, v2 offset:swizzle(SWAP,4)
	s_waitcnt lgkmcnt(1)
	v_add_f32_e32 v1, v14, v1
	ds_swizzle_b32 v5, v1 offset:swizzle(SWAP,2)
	ds_swizzle_b32 v11, v18 offset:swizzle(SWAP,1)
	v_fmac_f32_e32 v0, v10, v4
	s_waitcnt lgkmcnt(2)
	v_add_f32_e32 v2, v2, v3
	ds_swizzle_b32 v3, v2 offset:swizzle(SWAP,8)
	s_waitcnt lgkmcnt(2)
	v_add_f32_e32 v1, v1, v5
	ds_swizzle_b32 v5, v1 offset:swizzle(SWAP,4)
	v_mul_f32_e32 v4, v9, v7
	v_fmac_f32_e32 v4, v8, v6
	v_add_f32_e32 v0, v0, v4
	s_waitcnt lgkmcnt(2)
	v_add_f32_e32 v11, v18, v11
	s_waitcnt lgkmcnt(1)
	v_add_f32_e32 v2, v2, v3
	s_waitcnt lgkmcnt(0)
	v_add_f32_e32 v4, v1, v5
	v_add_f32_e32 v10, v12, v0
	ds_swizzle_b32 v12, v11 offset:swizzle(SWAP,2)
	ds_swizzle_b32 v3, v2 offset:swizzle(SWAP,16)
	ds_swizzle_b32 v5, v4 offset:swizzle(SWAP,8)
	ds_swizzle_b32 v6, v15 offset:swizzle(SWAP,1)
	ds_swizzle_b32 v8, v17 offset:swizzle(SWAP,1)
	s_waitcnt lgkmcnt(4)
	v_add_f32_e32 v11, v11, v12
	s_waitcnt lgkmcnt(3)
	v_add_f32_e32 v0, v2, v3
	s_waitcnt lgkmcnt(2)
	v_add_f32_e32 v2, v4, v5
	s_waitcnt lgkmcnt(1)
	v_add_f32_e32 v4, v15, v6
	ds_swizzle_b32 v6, v16 offset:swizzle(SWAP,1)
	ds_swizzle_b32 v12, v13 offset:swizzle(SWAP,1)
	ds_swizzle_b32 v14, v11 offset:swizzle(SWAP,4)
	ds_swizzle_b32 v15, v10 offset:swizzle(SWAP,1)
	s_waitcnt lgkmcnt(4)
	v_add_f32_e32 v8, v17, v8
	s_waitcnt lgkmcnt(3)
	v_add_f32_e32 v6, v16, v6
	s_waitcnt lgkmcnt(2)
	v_add_f32_e32 v12, v13, v12
	s_waitcnt lgkmcnt(1)
	v_add_f32_e32 v11, v11, v14
	s_waitcnt lgkmcnt(0)
	v_add_f32_e32 v10, v10, v15
	ds_swizzle_b32 v5, v4 offset:swizzle(SWAP,2)
	ds_swizzle_b32 v7, v6 offset:swizzle(SWAP,2)
	ds_swizzle_b32 v9, v8 offset:swizzle(SWAP,2)
	ds_swizzle_b32 v13, v12 offset:swizzle(SWAP,2)
	ds_swizzle_b32 v14, v11 offset:swizzle(SWAP,8)
	ds_swizzle_b32 v15, v10 offset:swizzle(SWAP,2)
	s_waitcnt lgkmcnt(5)
	v_add_f32_e32 v4, v4, v5
	s_waitcnt lgkmcnt(4)
	v_add_f32_e32 v6, v6, v7
	s_waitcnt lgkmcnt(3)
	v_add_f32_e32 v8, v8, v9
	s_waitcnt lgkmcnt(2)
	v_add_f32_e32 v12, v12, v13
	s_waitcnt lgkmcnt(1)
	v_add_f32_e32 v11, v11, v14
	s_waitcnt lgkmcnt(0)
	v_add_f32_e32 v15, v10, v15
	ds_swizzle_b32 v5, v4 offset:swizzle(SWAP,4)
	ds_swizzle_b32 v7, v6 offset:swizzle(SWAP,4)
	ds_swizzle_b32 v9, v8 offset:swizzle(SWAP,4)
	ds_swizzle_b32 v13, v12 offset:swizzle(SWAP,4)
	ds_swizzle_b32 v14, v11 offset:swizzle(SWAP,16)
	ds_swizzle_b32 v16, v15 offset:swizzle(SWAP,4)
	s_waitcnt lgkmcnt(5)
	v_add_f32_e32 v4, v4, v5
	s_waitcnt lgkmcnt(4)
	v_add_f32_e32 v6, v6, v7
	s_waitcnt lgkmcnt(3)
	v_add_f32_e32 v8, v8, v9
	s_waitcnt lgkmcnt(2)
	v_add_f32_e32 v12, v12, v13
	s_waitcnt lgkmcnt(1)
	v_add_f32_e32 v10, v11, v14
	s_waitcnt lgkmcnt(0)
	v_add_f32_e32 v14, v15, v16
	ds_swizzle_b32 v5, v4 offset:swizzle(SWAP,8)
	ds_swizzle_b32 v7, v6 offset:swizzle(SWAP,8)
	ds_swizzle_b32 v9, v8 offset:swizzle(SWAP,8)
	ds_swizzle_b32 v13, v12 offset:swizzle(SWAP,8)
	ds_swizzle_b32 v15, v14 offset:swizzle(SWAP,8)
	s_waitcnt lgkmcnt(4)
	v_add_f32_e32 v4, v4, v5
	s_waitcnt lgkmcnt(3)
	v_add_f32_e32 v6, v6, v7
	s_waitcnt lgkmcnt(2)
	v_add_f32_e32 v8, v8, v9
	s_waitcnt lgkmcnt(1)
	v_add_f32_e32 v12, v12, v13
	s_waitcnt lgkmcnt(0)
	v_add_f32_e32 v14, v14, v15
	ds_swizzle_b32 v3, v2 offset:swizzle(SWAP,16)
	ds_swizzle_b32 v5, v4 offset:swizzle(SWAP,16)
	ds_swizzle_b32 v7, v6 offset:swizzle(SWAP,16)
	ds_swizzle_b32 v9, v8 offset:swizzle(SWAP,16)
	ds_swizzle_b32 v13, v12 offset:swizzle(SWAP,16)
	ds_swizzle_b32 v15, v14 offset:swizzle(SWAP,16)
	s_waitcnt lgkmcnt(5)
	v_add_f32_e32 v2, v2, v3
	s_waitcnt lgkmcnt(4)
	v_add_f32_e32 v4, v4, v5
	s_waitcnt lgkmcnt(3)
	v_add_f32_e32 v6, v6, v7
	s_waitcnt lgkmcnt(2)
	v_add_f32_e32 v8, v8, v9
	s_waitcnt lgkmcnt(1)
	v_add_f32_e32 v12, v12, v13
	s_waitcnt lgkmcnt(0)
	v_add_f32_e32 v14, v14, v15
	v_mov_b32_e32 v1, v0
	v_mov_b32_e32 v3, v2
	v_mov_b32_e32 v5, v4
	v_mov_b32_e32 v7, v6
	v_mov_b32_e32 v9, v8
	v_mov_b32_e32 v11, v10
	v_mov_b32_e32 v13, v12
	v_mov_b32_e32 v15, v14
	v_permlane32_swap_b32_e32 v0, v1
	v_permlane32_swap_b32_e32 v2, v3
	v_permlane32_swap_b32_e32 v4, v5
	v_permlane32_swap_b32_e32 v6, v7
	v_permlane32_swap_b32_e32 v8, v9
	v_permlane32_swap_b32_e32 v10, v11
	v_permlane32_swap_b32_e32 v12, v13
	v_permlane32_swap_b32_e32 v14, v15
	s_and_saveexec_b64 s[4:5], s[6:7]
	s_cbranch_execz .LBB0_527
; __device__ __forceinline__ void norm_phase(ArgP a, LAS unsigned char* lds, int l, bool final_, const int tid, const int bid) {
;     ...
;             for (int q = 1; q < 8; ++q) z = (lane == q) ? fd[q] : z;
;             if (lane < 8) { z += a->b_f[l * 8 + lane]; LOGF[(size_t)row * 8 + lane] = fminf(z, 0.f) - log1pf(__expf(-fabsf(z))); }
	v_readlane_b32 s22, v255, 23
	v_readlane_b32 s23, v255, 24
	s_load_dwordx2 s[22:23], s[22:23], 0x30
	v_add_f32_e32 v2, v2, v3
	v_add_f32_e32 v0, v0, v1
	v_add_f32_e32 v4, v4, v5
	v_cndmask_b32_e64 v0, v0, v2, s[20:21]
	s_waitcnt lgkmcnt(0)
	v_lshl_add_u64 v[16:17], v[28:29], 2, s[22:23]
	global_load_dword v16, v[16:17], off
	v_add_f32_e32 v6, v6, v7
	v_cndmask_b32_e64 v0, v0, v4, s[18:19]
	v_add_f32_e32 v8, v8, v9
	v_cndmask_b32_e64 v0, v0, v6, s[16:17]
	v_add_f32_e32 v10, v10, v11
	v_cndmask_b32_e64 v0, v0, v8, s[14:15]
	v_add_f32_e32 v12, v12, v13
	v_cndmask_b32_e64 v0, v0, v10, s[12:13]
	v_add_f32_e32 v14, v14, v15
	v_cndmask_b32_e64 v0, v0, v12, s[10:11]
	v_cndmask_b32_e64 v0, v0, v14, s[8:9]
	s_mov_b32 s22, 0xbfb8aa3b
	s_waitcnt vmcnt(0)
	v_add_f32_e32 v1, v0, v16
	v_mul_f32_e64 v0, |v1|, s22
	v_exp_f32_e32 v0, v0
	s_lshl_b64 s[22:23], s[2:3], 2
	s_mov_b32 s3, 0x3f2aaaab
	v_min_f32_e32 v1, 0, v1
	v_add_f32_e32 v4, 1.0, v0
	v_add_f32_e32 v5, -1.0, v4
	v_frexp_mant_f32_e32 v6, v4
	v_cvt_f64_f32_e32 v[2:3], v4
	v_sub_f32_e32 v7, v5, v4
	v_frexp_exp_i32_f64_e32 v2, v[2:3]
	v_cmp_gt_f32_e32 vcc, s3, v6
	v_sub_f32_e32 v5, v0, v5
	v_add_f32_e32 v3, 1.0, v7
	v_subbrev_co_u32_e32 v2, vcc, 0, v2, vcc
	v_add_f32_e32 v3, v5, v3
	v_sub_u32_e32 v5, 0, v2
	v_ldexp_f32 v4, v4, v5
	v_add_f32_e32 v6, -1.0, v4
	v_add_f32_e32 v7, 1.0, v4
	v_ldexp_f32 v3, v3, v5
	v_add_f32_e32 v5, 1.0, v6
	v_add_f32_e32 v8, -1.0, v7
	v_sub_f32_e32 v5, v4, v5
	v_sub_f32_e32 v4, v4, v8
	v_add_f32_e32 v8, v3, v5
	v_add_f32_e32 v3, v3, v4
	v_add_f32_e32 v10, v7, v3
	v_rcp_f32_e32 v11, v10
	v_add_f32_e32 v5, v6, v8
	v_sub_f32_e32 v6, v5, v6
	v_sub_f32_e32 v4, v10, v7
	v_mul_f32_e32 v13, v5, v11
	v_sub_f32_e32 v12, v8, v6
	v_mul_f32_e32 v6, v10, v13
	v_sub_f32_e32 v3, v3, v4
	v_fma_f32 v8, v13, v10, -v6
	v_fmac_f32_e32 v8, v13, v3
	v_add_f32_e32 v4, v6, v8
	v_sub_f32_e32 v7, v5, v4
	v_mov_b32_e32 v9, v4
	v_pk_add_f32 v[4:5], v[4:5], v[6:7] neg_lo:[0,1] neg_hi:[0,1]
	v_cvt_f32_i32_e32 v2, v2
	v_pk_add_f32 v[4:5], v[4:5], v[8:9] neg_lo:[0,1] neg_hi:[0,1]
	s_mov_b32 s3, 0x3f317218
	v_add_f32_e32 v5, v12, v5
	v_add_f32_e32 v4, v4, v5
	v_add_f32_e32 v5, v7, v4
	v_mul_f32_e32 v9, v11, v5
	v_mul_f32_e32 v6, v10, v9
	v_sub_f32_e32 v7, v7, v5
	v_add_f32_e32 v14, v13, v9
	v_fma_f32 v8, v9, v10, -v6
	v_add_f32_e32 v12, v4, v7
	v_sub_f32_e32 v4, v14, v13
	v_fmac_f32_e32 v8, v9, v3
	v_sub_f32_e32 v3, v9, v4
	v_add_f32_e32 v4, v6, v8
	v_sub_f32_e32 v7, v5, v4
	v_mov_b32_e32 v9, v4
	v_pk_add_f32 v[4:5], v[4:5], v[6:7] neg_lo:[0,1] neg_hi:[0,1]
	s_nop 0
	v_pk_add_f32 v[4:5], v[4:5], v[8:9] neg_lo:[0,1] neg_hi:[0,1]
	v_mov_b32_e32 v8, 0x3ecc95a3
	v_add_f32_e32 v5, v12, v5
	v_add_f32_e32 v4, v4, v5
	v_add_f32_e32 v4, v7, v4
	v_mul_f32_e32 v4, v11, v4
	v_add_f32_e32 v3, v3, v4
	v_add_f32_e32 v4, v14, v3
	v_mul_f32_e32 v6, v4, v4
	v_sub_f32_e32 v7, v4, v14
	v_fmamk_f32 v8, v6, 0x3e9b6dac, v8
	v_sub_f32_e32 v7, v3, v7
	v_mul_f32_e32 v3, v4, v6
	v_fmaak_f32 v183, v6, v8, 0x3f2aaada
	v_ldexp_f32 v9, v7, 1
	v_pk_mul_f32 v[6:7], v[2:3], v[182:183]
	v_ldexp_f32 v5, v4, 1
	v_fma_f32 v4, v2, s3, -v6
	v_fmac_f32_e32 v4, 0xb102e308, v2
	v_pk_add_f32 v[2:3], v[6:7], v[4:5]
	v_mov_b32_e32 v8, v6
	v_sub_f32_e32 v12, v3, v5
	v_pk_add_f32 v[10:11], v[2:3], v[6:7] neg_lo:[0,1] neg_hi:[0,1]
	v_sub_f32_e32 v6, v7, v12
	v_add_f32_e32 v9, v9, v6
	v_pk_add_f32 v[6:7], v[2:3], v[8:9]
	v_mov_b32_e32 v5, v2
	v_mov_b32_e32 v11, v7
	v_pk_add_f32 v[14:15], v[4:5], v[10:11] neg_lo:[0,1] neg_hi:[0,1]
	v_pk_add_f32 v[4:5], v[4:5], v[10:11]
	v_mov_b32_e32 v13, v2
	v_pk_add_f32 v[10:11], v[4:5], v[2:3] op_sel:[1,0] op_sel_hi:[0,1] neg_lo:[0,1] neg_hi:[0,1]
	v_mov_b32_e32 v12, v9
	v_mov_b32_e32 v8, v7
	v_mov_b32_e32 v9, v5
	v_pk_mov_b32 v[2:3], v[2:3], v[10:11] op_sel:[1,0]
	v_pk_add_f32 v[6:7], v[6:7], v[10:11] op_sel_hi:[1,0] neg_lo:[0,1] neg_hi:[0,1]
	v_pk_add_f32 v[2:3], v[8:9], v[2:3] neg_lo:[0,1] neg_hi:[0,1]
	v_mov_b32_e32 v6, v14
	v_pk_add_f32 v[2:3], v[12:13], v[2:3] neg_lo:[0,1] neg_hi:[0,1]
	v_mov_b32_e32 v15, v5
	v_pk_add_f32 v[6:7], v[6:7], v[2:3]
	s_mov_b32 s3, 0x7f800000
	v_pk_add_f32 v[8:9], v[6:7], v[6:7] op_sel:[0,1] op_sel_hi:[1,0]
	v_cmp_neq_f32_e32 vcc, s3, v0
	v_pk_add_f32 v[4:5], v[4:5], v[8:9] op_sel:[1,0] op_sel_hi:[0,1]
	v_mov_b32_e32 v7, v4
	v_mov_b32_e32 v3, v8
	v_pk_add_f32 v[8:9], v[6:7], v[14:15] neg_lo:[0,1] neg_hi:[0,1]
	s_mov_b32 s3, 0x33800000
	v_sub_f32_e32 v5, v6, v8
	v_pk_add_f32 v[2:3], v[2:3], v[8:9] neg_lo:[0,1] neg_hi:[0,1]
	v_sub_f32_e32 v5, v14, v5
	v_add_f32_e32 v2, v2, v5
	v_add_f32_e32 v2, v2, v3
	v_add_f32_e32 v2, v4, v2
	v_cndmask_b32_e32 v2, v201, v2, vcc
	v_cmp_ngt_f32_e32 vcc, -1.0, v0
	s_nop 1
	v_cndmask_b32_e32 v2, v204, v2, vcc
	v_cmp_neq_f32_e32 vcc, -1.0, v0
	s_nop 1
	v_cndmask_b32_e32 v2, v205, v2, vcc
	v_cmp_lt_f32_e64 vcc, |v0|, s3
	s_nop 1
	v_cndmask_b32_e32 v0, v2, v0, vcc
	v_sub_f32_e32 v2, v1, v0
	v_lshl_add_u64 v[0:1], v[30:31], 0, s[22:23]
	global_store_dword v[0:1], v2, off
	s_branch .LBB0_527
.LBB0_530:
	s_waitcnt vmcnt(0)
	v_mov_b32_e32 v0, v184
	s_waitcnt lgkmcnt(0)
	s_barrier
